# prep: section B's first 12 loads and their address arithmetic are issued before wave 0 runs section A (registers of A renamed), so the load latency overlaps A
# baseline (speedup 1.0000x reference)
.LBB0_310:
	v_mov_b32_e32 v135, v206
	v_mov_b32_e32 v182, v211
	v_and_b32_e32 v2, 64, v211
	s_mov_b64 s[0:1], -1
	v_readfirstlane_b32 s24, v135
	s_cmp_lt_u32 s24, 64
	s_cbranch_scc1 .LBB0_312
	v_mbcnt_hi_u32_b32 v182, -1, v207
	v_and_b32_e32 v2, 64, v182
	s_mov_b64 s[0:1], 0

.LBB0_316:
	v_ashrrev_i32_e32 v181, 3, v135
	s_lshr_b32 s0, s23, 7
	v_and_b32_e32 v183, -2, v181
	v_and_b32_e32 v1, 15, v135
	s_lshl_b32 s0, s0, 6
	v_add3_u32 v60, s7, -3, v183
	v_lshlrev_b32_e32 v3, 3, v1
	s_and_b32 s0, s0, 0x180
	v_max_i32_e32 v16, -2, v60
	v_add_u32_e32 v62, s7, v183
	v_or_b32_e32 v61, s0, v3
	v_add_u32_e32 v16, 2, v16
	v_mov_b32_e32 v17, v0
	v_max_i32_e32 v20, 0, v62
	v_mov_b32_e32 v21, v0
	v_lshlrev_b32_e32 v28, 1, v61
	v_mov_b32_e32 v29, v0
	v_max_i32_e32 v12, -1, v60
	v_lshl_add_u64 v[16:17], s[4:5], 0, v[16:17]
	v_lshl_add_u64 v[20:21], s[4:5], 0, v[20:21]
	v_max_i32_e32 v26, -4, v60
	v_lshl_add_u64 v[24:25], s[12:13], 0, v[28:29]
	v_max_i32_e32 v8, 0, v60
	v_mov_b32_e32 v9, v0
	v_add_u32_e32 v12, 1, v12
	v_mov_b32_e32 v13, v0
	v_lshlrev_b64 v[36:37], 12, v[16:17]
	v_lshlrev_b64 v[40:41], 12, v[20:21]
	v_add_u32_e32 v26, 4, v26
	v_mov_b32_e32 v27, v0
	v_lshl_add_u64 v[8:9], s[4:5], 0, v[8:9]
	v_lshl_add_u64 v[12:13], s[4:5], 0, v[12:13]
	v_lshl_add_u64 v[16:17], v[24:25], 0, v[36:37]
	v_lshl_add_u64 v[20:21], v[24:25], 0, v[40:41]
	v_lshl_add_u64 v[26:27], s[4:5], 0, v[26:27]
	v_lshlrev_b64 v[30:31], 12, v[8:9]
	v_lshlrev_b64 v[32:33], 12, v[12:13]
	global_load_dwordx4 v[16:19], v[16:17], off
	v_lshlrev_b64 v[44:45], 12, v[26:27]
	global_load_dwordx4 v[20:23], v[20:21], off
	v_lshl_add_u64 v[8:9], v[24:25], 0, v[30:31]
	v_lshl_add_u64 v[12:13], v[24:25], 0, v[32:33]
	v_lshl_add_u64 v[24:25], v[24:25], 0, v[44:45]
	global_load_dwordx4 v[24:27], v[24:25], off
	v_mov_b32_e32 v47, v0
	global_load_dwordx4 v[8:11], v[8:9], off
	v_or_b32_e32 v46, 0x400, v28
	global_load_dwordx4 v[12:15], v[12:13], off
	v_lshl_add_u64 v[54:55], s[12:13], 0, v[40:41]
	v_lshl_add_u64 v[40:41], v[54:55], 0, v[46:47]
	v_lshl_add_u64 v[58:59], s[12:13], 0, v[44:45]
	v_lshl_add_u64 v[48:49], s[12:13], 0, v[30:31]
	v_lshl_add_u64 v[50:51], s[12:13], 0, v[32:33]
	v_lshl_add_u64 v[52:53], s[12:13], 0, v[36:37]
	global_load_dwordx4 v[40:43], v[40:41], off
	v_lshl_add_u64 v[44:45], v[58:59], 0, v[46:47]
	v_lshl_add_u64 v[28:29], v[48:49], 0, v[46:47]
	v_lshl_add_u64 v[32:33], v[50:51], 0, v[46:47]
	v_lshl_add_u64 v[36:37], v[52:53], 0, v[46:47]
	global_load_dwordx4 v[44:47], v[44:45], off
	v_cmp_gt_i32_e64 s[4:5], 0, v62
	v_readlane_b32 s34, v251, 51
	v_lshl_or_b32 v3, s6, 7, v3
	v_readlane_b32 s35, v251, 52
	v_or_b32_e32 v3, 0x400, v3
	v_cmp_gt_i32_e64 s[6:7], -4, v60
	global_load_dwordx4 v[28:31], v[28:29], off
	v_mov_b32_e32 v57, v0
	v_lshlrev_b32_e32 v56, 1, v3
	v_lshl_add_u64 v[48:49], v[48:49], 0, v[56:57]
	v_cmp_gt_i32_e32 vcc, 0, v60
	v_cmp_gt_i32_e64 s[0:1], -1, v60
	v_cmp_gt_i32_e64 s[2:3], -2, v60
	s_movk_i32 s25, 0x4000
	global_load_dwordx4 v[32:35], v[32:33], off
	v_lshl_add_u64 v[50:51], v[50:51], 0, v[56:57]
	global_load_dwordx4 v[36:39], v[36:37], off
	s_nop 0
	global_load_dwordx4 v[104:107], v[48:49], off
	global_load_dwordx4 v[108:111], v[50:51], off
	s_mov_b64 s[28:29], 0x2000
	s_movk_i32 s26, 0x6000
	s_mov_b64 s[30:31], 0x6000
	v_add_u32_e32 v201, 64, v2
	v_lshlrev_b32_e32 v197, 4, v1
	v_lshrrev_b32_e32 v198, 5, v135
	v_bfe_u32 v200, v135, 2, 2
	s_cmp_lt_u32 s24, 64
	s_cbranch_scc0 .Lpa_bar
	s_mov_b64 s[36:37], s[0:1]
	s_mov_b64 s[38:39], s[2:3]
	s_mov_b64 s[40:41], s[4:5]
	s_mov_b64 s[42:43], s[6:7]
	s_mov_b64 s[44:45], vcc
	v_cmp_gt_u32_e64 s[0:1], 32, v134
	v_add_u32_e32 v236, -1, v211
	v_add_u32_e32 v237, -2, v211
	v_add_u32_e32 v238, -4, v211
	v_add_u32_e32 v239, -8, v211
	s_nop 0
	v_and_b32_e32 v2, 64, v211
	v_cmp_lt_i32_e32 vcc, v236, v2
	v_add_u32_e32 v240, -16, v211
	v_subrev_u32_e32 v241, 32, v211
	v_cndmask_b32_e32 v236, v236, v211, vcc
	v_cmp_lt_i32_e32 vcc, v237, v2
	s_mov_b32 s2, 0x3f317217
	v_lshlrev_b32_e32 v236, 2, v236
	v_cndmask_b32_e32 v237, v237, v211, vcc
	v_cmp_lt_i32_e32 vcc, v238, v2
	v_lshlrev_b32_e32 v237, 2, v237
	v_lshl_add_u32 v4, v134, 2, 0
	v_cndmask_b32_e32 v238, v238, v211, vcc
	v_cmp_lt_i32_e32 vcc, v239, v2
	v_lshlrev_b32_e32 v238, 2, v238
	v_add_u32_e32 v5, 0x20500, v4
	v_cndmask_b32_e32 v239, v239, v211, vcc
	v_cmp_lt_i32_e32 vcc, v240, v2
	v_lshlrev_b32_e32 v239, 2, v239
	v_add_u32_e32 v4, 0x20600, v4
	v_cndmask_b32_e32 v240, v240, v211, vcc
	v_cmp_lt_i32_e32 vcc, v241, v2
	s_waitcnt vmcnt(20)
	v_mov_b32_e32 v246, v242
	v_mov_b32_e32 v235, v244
	v_mov_b32_e32 v234, v245
	v_mov_b32_e32 v247, v243
	v_add_f32_e32 v246, v246, v235
	v_mul_f32_e32 v235, 0x3fb8aa3b, v246
	v_exp_f32_e32 v235, v235
	v_cndmask_b32_e32 v241, v241, v211, vcc
	v_mul_f32_e32 v234, 0x3fb8aa3b, v234
	v_exp_f32_e32 v234, v234
	v_add_f32_e32 v235, 1.0, v235
	v_cmp_gt_f32_e32 vcc, s51, v235
	v_mul_f32_e32 v247, 0xbfb8aa3b, v247
	v_exp_f32_e32 v247, v247
	v_cndmask_b32_e64 v6, 0, 32, vcc
	v_ldexp_f32 v235, v235, v6
	v_log_f32_e32 v235, v235
	v_cndmask_b32_e32 v6, 0, v213, vcc
	v_add_f32_e32 v247, 1.0, v247
	v_mul_f32_e32 v7, 0x3f317217, v235
	v_fma_f32 v7, v235, s2, -v7
	v_fmac_f32_e32 v7, 0x3377d1cf, v235
	s_mov_b32 s2, 0x7f800000
	v_fmac_f32_e32 v7, 0x3f317217, v235
	v_cmp_lt_f32_e64 vcc, |v235|, s2
	s_mov_b32 s2, 0x41a00000
	s_nop 0
	v_cndmask_b32_e32 v235, v235, v7, vcc
	v_sub_f32_e32 v235, v235, v6
	v_cmp_lt_f32_e32 vcc, s2, v246
	s_nop 1
	v_cndmask_b32_e32 v246, v235, v246, vcc
	v_mul_f32_e64 v235, v246, -v234
	ds_bpermute_b32 v236, v236, v235
	v_cmp_eq_u32_e32 vcc, 0, v134
	s_waitcnt lgkmcnt(0)
	v_fma_f32 v246, v246, -v234, v236
	v_cndmask_b32_e32 v246, v246, v235, vcc
	ds_bpermute_b32 v234, v237, v246
	v_cmp_gt_u32_e32 vcc, 2, v134
	v_div_scale_f32 v237, s[2:3], v247, v247, 1.0
	v_cmp_gt_u32_e64 s[2:3], 8, v134
	s_waitcnt lgkmcnt(0)
	v_add_f32_e32 v234, v246, v234
	v_cndmask_b32_e32 v246, v234, v246, vcc
	ds_bpermute_b32 v234, v238, v246
	v_cmp_gt_u32_e32 vcc, 4, v134
	v_lshlrev_b32_e32 v235, 2, v240
	v_rcp_f32_e32 v238, v237
	v_lshlrev_b32_e32 v236, 2, v241
	s_waitcnt lgkmcnt(0)
	v_add_f32_e32 v234, v246, v234
	v_cndmask_b32_e32 v246, v234, v246, vcc
	ds_bpermute_b32 v234, v239, v246
	v_fma_f32 v240, -v237, v238, 1.0
	v_div_scale_f32 v239, vcc, 1.0, v247, 1.0
	v_fmac_f32_e32 v238, v240, v238
	s_waitcnt lgkmcnt(0)
	v_add_f32_e32 v234, v246, v234
	v_cndmask_b32_e64 v246, v234, v246, s[2:3]
	ds_bpermute_b32 v234, v235, v246
	v_cmp_gt_u32_e64 s[2:3], 16, v134
	v_mul_f32_e32 v235, v239, v238
	v_fma_f32 v240, -v237, v235, v239
	v_fmac_f32_e32 v235, v240, v238
	s_waitcnt lgkmcnt(0)
	v_add_f32_e32 v234, v246, v234
	v_cndmask_b32_e64 v234, v234, v246, s[2:3]
	ds_bpermute_b32 v246, v236, v234
	v_fma_f32 v237, -v237, v235, v239
	v_div_fmas_f32 v235, v237, v238, v235
	v_div_fixup_f32 v247, v235, v247, 1.0
	ds_write_b32 v4, v247
	s_waitcnt lgkmcnt(1)
	v_add_f32_e32 v246, v234, v246
	v_cndmask_b32_e64 v247, v246, v234, s[0:1]
	v_cmp_eq_u32_e32 vcc, 63, v134
	ds_write_b32 v5, v247
	s_and_saveexec_b64 s[0:1], vcc
	s_cbranch_execz .LBB0_315
	v_mul_f32_e32 v246, 0x3fb8aa3b, v246
	v_exp_f32_e32 v246, v246
	s_add_u32 s2, s10, s20
	s_addc_u32 s3, s11, s21
	global_store_dword v0, v246, s[2:3]
.LBB0_315:
	s_or_b64 exec, exec, s[0:1]
	v_mov_b32_e32 v182, v211
	s_mov_b64 s[0:1], s[36:37]
	s_mov_b64 s[2:3], s[38:39]
	s_mov_b64 s[4:5], s[40:41]
	s_mov_b64 s[6:7], s[42:43]
	s_mov_b64 vcc, s[44:45]
.Lpa_bar:
	s_waitcnt lgkmcnt(0)
	s_barrier
	s_waitcnt vmcnt(11)
	v_cndmask_b32_e64 v161, v16, 0, s[2:3]
	v_cndmask_b32_e64 v129, v17, 0, s[2:3]
	s_waitcnt vmcnt(10)
	v_cndmask_b32_e64 v163, v20, 0, s[4:5]
	v_cndmask_b32_e64 v131, v21, 0, s[4:5]
	v_lshlrev_b32_e32 v20, 2, v61
	v_mov_b32_e32 v21, v0
	v_cndmask_b32_e64 v125, v22, 0, s[4:5]
	v_cndmask_b32_e64 v117, v23, 0, s[4:5]
	v_lshl_add_u64 v[22:23], s[34:35], 0, v[20:21]
	s_waitcnt vmcnt(9)
	v_cndmask_b32_e64 v202, v26, 0, s[6:7]
	v_add_co_u32_e64 v26, s[8:9], s62, v22
	v_cndmask_b32_e64 v203, v27, 0, s[6:7]
	s_nop 0
	v_addc_co_u32_e64 v27, s[8:9], 0, v23, s[8:9]
	s_waitcnt vmcnt(8)
	v_cndmask_b32_e64 v165, v8, 0, vcc
	v_cndmask_b32_e64 v118, v9, 0, vcc
	s_waitcnt vmcnt(7)
	v_cndmask_b32_e64 v133, v12, 0, s[0:1]
	v_cndmask_b32_e64 v127, v13, 0, s[0:1]
	v_lshl_add_u64 v[8:9], v[52:53], 0, v[56:57]
	v_lshl_add_u64 v[12:13], v[54:55], 0, v[56:57]
	v_lshl_add_u64 v[16:17], v[58:59], 0, v[56:57]
	v_add_co_u32_e64 v48, s[8:9], s25, v22
	v_cndmask_b32_e64 v119, v10, 0, vcc
	v_cndmask_b32_e64 v120, v11, 0, vcc
	v_cndmask_b32_e64 v121, v14, 0, s[0:1]
	v_cndmask_b32_e64 v113, v15, 0, s[0:1]
	v_cndmask_b32_e64 v123, v18, 0, s[2:3]
	v_cndmask_b32_e64 v115, v19, 0, s[2:3]
	global_load_dwordx4 v[8:11], v[8:9], off
	v_cndmask_b32_e64 v196, v24, 0, s[6:7]
	global_load_dwordx4 v[12:15], v[12:13], off
	v_cndmask_b32_e64 v199, v25, 0, s[6:7]
	global_load_dwordx4 v[16:19], v[16:17], off
	s_nop 0
	global_load_dwordx4 v[72:75], v20, s[34:35]
	global_load_dwordx4 v[88:91], v20, s[34:35] offset:16
	v_lshl_add_u64 v[24:25], v[22:23], 0, s[28:29]
	v_addc_co_u32_e64 v49, s[8:9], 0, v23, s[8:9]
	global_load_dwordx4 v[76:79], v[26:27], off
	global_load_dwordx4 v[92:95], v[24:25], off offset:16
	v_lshl_add_u64 v[24:25], v[22:23], 0, s[48:49]
	v_add_co_u32_e64 v52, s[8:9], s26, v22
	global_load_dwordx4 v[96:99], v[24:25], off offset:16
	s_nop 0
	v_addc_co_u32_e64 v53, s[8:9], 0, v23, s[8:9]
	v_lshl_add_u64 v[24:25], v[22:23], 0, s[30:31]
	global_load_dwordx4 v[80:83], v[52:53], off
	global_load_dwordx4 v[100:103], v[24:25], off offset:16
	s_mov_b64 s[8:9], 0x2800
	s_waitcnt vmcnt(16)
	v_cndmask_b32_e64 v180, v40, 0, s[4:5]
	v_cndmask_b32_e64 v187, v41, 0, s[4:5]
	v_cndmask_b32_e64 v191, v42, 0, s[4:5]
	v_cndmask_b32_e64 v195, v43, 0, s[4:5]
	global_load_dwordx4 v[40:43], v20, s[34:35] offset:2048
	global_load_dwordx4 v[56:59], v20, s[34:35] offset:2064
	v_lshl_add_u64 v[20:21], v[22:23], 0, s[8:9]
	s_mov_b64 s[8:9], 0x4800
	s_waitcnt vmcnt(17)
	v_cndmask_b32_e64 v172, v44, 0, s[6:7]
	v_cndmask_b32_e64 v174, v45, 0, s[6:7]
	v_cndmask_b32_e64 v175, v46, 0, s[6:7]
	v_cndmask_b32_e64 v176, v47, 0, s[6:7]
	global_load_dwordx4 v[44:47], v[26:27], off offset:2048
	v_lshl_add_u64 v[24:25], v[22:23], 0, s[8:9]
	global_load_dwordx4 v[84:87], v[48:49], off
	s_nop 0
	global_load_dwordx4 v[48:51], v[48:49], off offset:2048
	s_nop 0
	global_load_dwordx4 v[64:67], v[20:21], off offset:16
	global_load_dwordx4 v[68:71], v[24:25], off offset:16
	s_waitcnt vmcnt(18)
	v_cndmask_b32_e64 v148, v105, 0, vcc
	v_cndmask_b32_e64 v168, v104, 0, vcc
	v_lshlrev_b32_e32 v104, 16, v120
	v_and_b32_e32 v105, 0xffff0000, v120
	v_lshlrev_b32_e32 v112, 16, v113
	v_and_b32_e32 v113, 0xffff0000, v113
	v_lshlrev_b32_e32 v114, 16, v115
	v_and_b32_e32 v115, 0xffff0000, v115
	v_lshlrev_b32_e32 v116, 16, v117
	v_and_b32_e32 v117, 0xffff0000, v117
	s_mov_b64 s[8:9], 0x6800
	v_cndmask_b32_e64 v140, v107, 0, vcc
	v_lshl_add_u64 v[20:21], v[22:23], 0, s[8:9]
	v_cndmask_b32_e64 v144, v106, 0, vcc
	global_load_dwordx4 v[52:55], v[52:53], off offset:2048
	s_nop 0
	global_load_dwordx4 v[60:63], v[20:21], off offset:16
	v_cndmask_b32_e64 v177, v28, 0, vcc
	v_cndmask_b32_e64 v184, v29, 0, vcc
	v_cndmask_b32_e64 v188, v30, 0, vcc
	v_cndmask_b32_e64 v192, v31, 0, vcc
	v_cndmask_b32_e64 v178, v32, 0, s[0:1]
	v_cndmask_b32_e64 v185, v33, 0, s[0:1]
	v_cndmask_b32_e64 v189, v34, 0, s[0:1]
	v_cndmask_b32_e64 v193, v35, 0, s[0:1]
	s_waitcnt vmcnt(19)
	v_cndmask_b32_e64 v141, v111, 0, s[0:1]
	v_cndmask_b32_e64 v145, v110, 0, s[0:1]
	v_cndmask_b32_e64 v149, v109, 0, s[0:1]
	v_cndmask_b32_e64 v169, v108, 0, s[0:1]
	v_xor_b32_e32 v108, 1, v182
	v_lshlrev_b32_e32 v120, 16, v121
	v_and_b32_e32 v121, 0xffff0000, v121
	v_lshlrev_b32_e32 v122, 16, v123
	v_and_b32_e32 v123, 0xffff0000, v123
	v_lshlrev_b32_e32 v124, 16, v125
	v_and_b32_e32 v125, 0xffff0000, v125
	v_lshlrev_b32_e32 v130, 16, v131
	v_and_b32_e32 v131, 0xffff0000, v131
	v_cndmask_b32_e64 v179, v36, 0, s[2:3]
	v_cndmask_b32_e64 v186, v37, 0, s[2:3]
	v_cndmask_b32_e64 v190, v38, 0, s[2:3]
	v_cndmask_b32_e64 v194, v39, 0, s[2:3]
	s_waitcnt vmcnt(18)
	v_cndmask_b32_e64 v142, v11, 0, s[2:3]
	v_cndmask_b32_e64 v146, v10, 0, s[2:3]
	s_waitcnt vmcnt(17)
	v_cndmask_b32_e64 v171, v12, 0, s[4:5]
	v_lshlrev_b32_e32 v12, 2, v3
	v_cndmask_b32_e64 v151, v13, 0, s[4:5]
	s_waitcnt vmcnt(14)
	v_pk_fma_f32 v[104:105], v[90:91], v[104:105], 0 op_sel_hi:[1,1,0]
	v_mov_b32_e32 v13, v0
	v_lshl_add_u64 v[20:21], s[34:35], 0, v[12:13]
	v_cndmask_b32_e64 v147, v14, 0, s[4:5]
	s_waitcnt vmcnt(12)
	v_pk_fma_f32 v[104:105], v[94:95], v[112:113], v[104:105]
	v_add_co_u32_e32 v14, vcc, s62, v20
	v_cndmask_b32_e64 v143, v15, 0, s[4:5]
	s_waitcnt vmcnt(11)
	v_pk_fma_f32 v[104:105], v[98:99], v[114:115], v[104:105]
	v_addc_co_u32_e32 v15, vcc, 0, v21, vcc
	v_cndmask_b32_e64 v137, v18, 0, s[6:7]
	s_waitcnt vmcnt(9)
	v_pk_fma_f32 v[104:105], v[102:103], v[116:117], v[104:105]
	v_add_co_u32_e32 v18, vcc, s25, v20
	v_mul_f32_e32 v3, 0xbfb8aa3b, v105
	v_exp_f32_e32 v107, v3
	v_mul_f32_e32 v3, 0xbfb8aa3b, v104
	v_exp_f32_e32 v106, v3
	v_cndmask_b32_e64 v136, v19, 0, s[6:7]
	v_addc_co_u32_e32 v19, vcc, 0, v21, vcc
	v_pk_add_f32 v[2:3], v[106:107], 1.0 op_sel_hi:[1,0]
	v_cndmask_b32_e64 v150, v9, 0, s[2:3]
	s_nop 0
	v_cndmask_b32_e64 v170, v8, 0, s[2:3]
	v_cndmask_b32_e64 v138, v17, 0, s[6:7]
	v_cndmask_b32_e64 v139, v16, 0, s[6:7]
	global_load_dwordx4 v[8:11], v12, s[34:35] offset:16
	global_load_dwordx4 v[24:27], v12, s[34:35]
	v_lshl_add_u64 v[12:13], v[20:21], 0, s[28:29]
	v_lshl_add_u64 v[16:17], v[20:21], 0, s[48:49]
	v_lshl_add_u64 v[22:23], v[20:21], 0, s[30:31]
	v_add_co_u32_e32 v20, vcc, s26, v20
	s_nop 0
	s_nop 0
	v_addc_co_u32_e32 v21, vcc, 0, v21, vcc
	v_cmp_lt_i32_e32 vcc, v108, v201
	v_pk_fma_f32 v[90:91], v[90:91], v[112:113], 0 op_sel_hi:[1,1,0]
	s_mov_b32 s4, 0x358637bd
	v_cndmask_b32_e32 v108, v182, v108, vcc
	v_lshlrev_b32_e32 v173, 2, v108
	s_nop 0
	s_nop 0
	s_nop 0
	s_nop 0
	s_nop 0
	s_nop 0
	s_nop 0
	s_nop 0
	s_nop 0
	s_nop 0
	v_rcp_f32_e32 v3, v3
	s_nop 0
	s_nop 0
	s_nop 0
	s_nop 0
	s_nop 0
	s_nop 0
	v_lshlrev_b32_e32 v106, 16, v119
	v_and_b32_e32 v107, 0xffff0000, v119
	v_pk_fma_f32 v[106:107], v[88:89], v[106:107], 0 op_sel_hi:[1,1,0]
	s_nop 0
	v_pk_fma_f32 v[106:107], v[92:93], v[120:121], v[106:107]
	s_nop 0
	v_pk_fma_f32 v[106:107], v[96:97], v[122:123], v[106:107]
	v_rcp_f32_e32 v2, v2
	v_pk_fma_f32 v[106:107], v[100:101], v[124:125], v[106:107]
	v_pk_fma_f32 v[90:91], v[94:95], v[114:115], v[90:91]
	v_mul_f32_e32 v108, 0xbfb8aa3b, v106
	v_mul_f32_e32 v109, 0xbfb8aa3b, v107
	v_exp_f32_e32 v108, v108
	v_exp_f32_e32 v109, v109
	v_pk_fma_f32 v[90:91], v[98:99], v[116:117], v[90:91]
	v_lshlrev_b32_e32 v94, 16, v203
	v_and_b32_e32 v95, 0xffff0000, v203
	v_pk_add_f32 v[108:109], v[108:109], 1.0 op_sel_hi:[1,0]
	v_pk_fma_f32 v[94:95], v[102:103], v[94:95], v[90:91]
	s_nop 0
	s_nop 0
	s_nop 0
	s_nop 0
	s_nop 0
	s_nop 0
	s_nop 0
	s_nop 0
	s_nop 0
	s_nop 0
	s_nop 0
	s_nop 0
	v_rcp_f32_e32 v109, v109
	s_nop 0
	s_nop 0
	s_nop 0
	s_nop 0
	s_nop 0
	s_nop 0
	v_lshlrev_b32_e32 v110, 16, v118
	v_and_b32_e32 v111, 0xffff0000, v118
	v_lshlrev_b32_e32 v126, 16, v127
	v_and_b32_e32 v127, 0xffff0000, v127
	v_pk_fma_f32 v[110:111], v[74:75], v[110:111], 0 op_sel_hi:[1,1,0]
	v_lshlrev_b32_e32 v128, 16, v129
	v_and_b32_e32 v129, 0xffff0000, v129
	v_pk_fma_f32 v[110:111], v[78:79], v[126:127], v[110:111]
	s_nop 0
	s_waitcnt vmcnt(7)
	v_pk_fma_f32 v[110:111], v[86:87], v[128:129], v[110:111]
	s_nop 0
	v_pk_fma_f32 v[110:111], v[82:83], v[130:131], v[110:111]
	v_rcp_f32_e32 v108, v108
	v_mul_f32_e32 v118, 0xbfb8aa3b, v110
	v_mul_f32_e32 v119, 0xbfb8aa3b, v111
	v_exp_f32_e32 v118, v118
	v_exp_f32_e32 v119, v119
	v_mul_f32_e32 v90, 0xbfb8aa3b, v95
	v_exp_f32_e32 v91, v90
	v_mul_f32_e32 v90, 0xbfb8aa3b, v94
	v_pk_add_f32 v[118:119], v[118:119], 1.0 op_sel_hi:[1,0]
	v_exp_f32_e32 v90, v90
	s_nop 0
	s_nop 0
	s_nop 0
	s_nop 0
	s_nop 0
	s_nop 0
	s_nop 0
	s_nop 0
	s_nop 0
	s_nop 0
	s_nop 0
	s_nop 0
	v_rcp_f32_e32 v119, v119
	s_nop 0
	s_nop 0
	s_nop 0
	s_nop 0
	s_nop 0
	v_lshlrev_b32_e32 v164, 16, v165
	v_and_b32_e32 v165, 0xffff0000, v165
	s_nop 0
	v_lshlrev_b32_e32 v132, 16, v133
	v_and_b32_e32 v133, 0xffff0000, v133
	v_pk_fma_f32 v[164:165], v[72:73], v[164:165], 0 op_sel_hi:[1,1,0]
	v_lshlrev_b32_e32 v160, 16, v161
	v_and_b32_e32 v161, 0xffff0000, v161
	v_pk_fma_f32 v[164:165], v[76:77], v[132:133], v[164:165]
	v_lshlrev_b32_e32 v162, 16, v163
	v_and_b32_e32 v163, 0xffff0000, v163
	v_pk_fma_f32 v[164:165], v[84:85], v[160:161], v[164:165]
	s_nop 0
	v_pk_fma_f32 v[164:165], v[80:81], v[162:163], v[164:165]
	s_nop 0
	v_mul_f32_e32 v204, 0xbfb8aa3b, v164
	v_mul_f32_e32 v205, 0xbfb8aa3b, v165
	v_exp_f32_e32 v204, v204
	v_exp_f32_e32 v205, v205
	v_rcp_f32_e32 v118, v118
	v_pk_fma_f32 v[88:89], v[88:89], v[120:121], 0 op_sel_hi:[1,1,0]
	v_pk_fma_f32 v[74:75], v[74:75], v[126:127], 0 op_sel_hi:[1,1,0]
	v_pk_add_f32 v[204:205], v[204:205], 1.0 op_sel_hi:[1,0]
	v_pk_fma_f32 v[88:89], v[92:93], v[122:123], v[88:89]
	s_nop 0
	s_nop 0
	v_pk_fma_f32 v[88:89], v[96:97], v[124:125], v[88:89]
	v_lshlrev_b32_e32 v92, 16, v202
	v_and_b32_e32 v93, 0xffff0000, v202
	s_nop 0
	s_nop 0
	s_nop 0
	s_nop 0
	s_nop 0
	s_nop 0
	s_nop 0
	s_nop 0
	s_nop 0
	s_nop 0
	v_rcp_f32_e32 v205, v205
	v_pk_fma_f32 v[92:93], v[100:101], v[92:93], v[88:89]
	s_nop 0
	s_nop 0
	s_nop 0
	s_nop 0
	s_nop 0
	s_nop 0
	s_nop 0
	s_nop 0
	v_pk_add_f32 v[98:99], v[90:91], 1.0 op_sel_hi:[1,0]
	v_mul_f32_e32 v88, 0xbfb8aa3b, v92
	s_nop 0
	s_nop 0
	v_mul_f32_e32 v89, 0xbfb8aa3b, v93
	v_exp_f32_e32 v88, v88
	v_exp_f32_e32 v89, v89
	s_nop 0
	s_nop 0
	s_nop 0
	s_nop 0
	s_nop 0
	s_nop 0
	s_nop 0
	s_nop 0
	s_nop 0
	s_nop 0
	v_rcp_f32_e32 v99, v99
	v_pk_fma_f32 v[74:75], v[78:79], v[128:129], v[74:75]
	s_nop 0
	s_nop 0
	s_nop 0
	s_nop 0
	s_nop 0
	s_nop 0
	s_nop 0
	s_nop 0
	v_pk_add_f32 v[96:97], v[88:89], 1.0 op_sel_hi:[1,0]
	v_rcp_f32_e32 v98, v98
	s_nop 0
	s_nop 0
	v_pk_mul_f32 v[88:89], v[94:95], v[98:99]
	v_pk_fma_f32 v[74:75], v[86:87], v[130:131], v[74:75]
	v_lshlrev_b32_e32 v78, 16, v199
	s_nop 0
	s_nop 0
	s_nop 0
	s_nop 0
	s_nop 0
	s_nop 0
	s_nop 0
	s_nop 0
	s_nop 0
	v_and_b32_e32 v79, 0xffff0000, v199
	v_pk_fma_f32 v[74:75], v[82:83], v[78:79], v[74:75]
	s_nop 0
	v_mul_f32_e32 v78, 0xbfb8aa3b, v74
	v_mul_f32_e32 v79, 0xbfb8aa3b, v75
	v_rcp_f32_e32 v97, v97
	s_nop 0
	v_exp_f32_e32 v78, v78
	v_exp_f32_e32 v79, v79
	s_nop 0
	s_nop 0
	s_nop 0
	s_nop 0
	s_nop 0
	v_pk_add_f32 v[78:79], v[78:79], 1.0 op_sel_hi:[1,0]
	s_nop 0
	s_nop 0
	s_nop 0
	s_nop 0
	v_rcp_f32_e32 v96, v96
	s_nop 0
	v_pk_mul_f32 v[82:83], v[92:93], v[96:97]
	v_pk_fma_f32 v[72:73], v[72:73], v[132:133], 0 op_sel_hi:[1,1,0]
	s_nop 0
	s_nop 0
	s_nop 0
	s_nop 0
	s_nop 0
	v_pk_fma_f32 v[72:73], v[76:77], v[160:161], v[72:73]
	s_nop 0
	s_nop 0
	v_pk_fma_f32 v[72:73], v[84:85], v[162:163], v[72:73]
	v_lshlrev_b32_e32 v76, 16, v196
	v_and_b32_e32 v77, 0xffff0000, v196
	s_nop 0
	v_pk_fma_f32 v[72:73], v[80:81], v[76:77], v[72:73]
	s_nop 0
	v_mul_f32_e32 v76, 0xbfb8aa3b, v72
	v_mul_f32_e32 v77, 0xbfb8aa3b, v73
	v_exp_f32_e32 v76, v76
	v_exp_f32_e32 v77, v77
	s_nop 0
	v_rcp_f32_e32 v79, v79
	s_nop 0
	s_nop 0
	s_nop 0
	s_nop 0
	v_pk_add_f32 v[76:77], v[76:77], 1.0 op_sel_hi:[1,0]
	s_nop 0
	s_nop 0
	s_nop 0
	s_nop 0
	s_nop 0
	s_nop 0
	v_rcp_f32_e32 v78, v78
	s_nop 0
	v_pk_mul_f32 v[80:81], v[74:75], v[78:79]
	s_nop 0
	s_nop 0
	s_nop 0
	s_nop 0
	s_nop 0
	s_nop 0
	s_nop 0
	s_nop 0
	s_nop 0
	s_nop 0
	v_rcp_f32_e32 v77, v77
	v_rcp_f32_e32 v204, v204
	s_nop 0
	s_nop 0
	s_nop 0
	s_nop 0
	s_nop 0
	s_nop 0
	s_nop 0
	s_nop 0
	v_rcp_f32_e32 v76, v76
	v_pk_mul_f32 v[90:91], v[164:165], v[204:205]
	v_pk_mul_f32 v[84:85], v[72:73], v[76:77]
	v_pk_mul_f32 v[110:111], v[110:111], v[118:119]
	v_pk_mul_f32 v[102:103], v[90:91], v[90:91]
	v_pk_mul_f32 v[72:73], v[84:85], v[84:85]
	v_pk_mul_f32 v[118:119], v[110:111], v[110:111]
	v_pk_mul_f32 v[74:75], v[80:81], v[80:81]
	v_mov_b32_e32 v76, v72
	v_mov_b32_e32 v77, v102
	v_mov_b32_e32 v102, v73
	v_pk_mul_f32 v[106:107], v[106:107], v[108:109]
	v_pk_add_f32 v[72:73], v[76:77], v[102:103]
	v_mov_b32_e32 v76, v74
	v_mov_b32_e32 v77, v118
	v_pk_mul_f32 v[108:109], v[106:107], v[106:107]
	v_pk_mul_f32 v[86:87], v[82:83], v[82:83]
	v_pk_add_f32 v[72:73], v[76:77], v[72:73]
	v_mov_b32_e32 v118, v75
	v_pk_mul_f32 v[2:3], v[104:105], v[2:3]
	v_pk_add_f32 v[72:73], v[118:119], v[72:73]
	v_mov_b32_e32 v74, v86
	v_mov_b32_e32 v75, v108
	v_pk_mul_f32 v[104:105], v[2:3], v[2:3]
	v_pk_mul_f32 v[94:95], v[88:89], v[88:89]
	v_pk_add_f32 v[72:73], v[74:75], v[72:73]
	v_mov_b32_e32 v108, v87
	v_pk_add_f32 v[72:73], v[108:109], v[72:73]
	v_mov_b32_e32 v74, v94
	v_mov_b32_e32 v75, v104
	v_pk_add_f32 v[72:73], v[74:75], v[72:73]
	v_mov_b32_e32 v104, v95
	v_pk_add_f32 v[72:73], v[104:105], v[72:73]
	ds_bpermute_b32 v75, v173, v73
	ds_bpermute_b32 v74, v173, v72
	v_xor_b32_e32 v76, 2, v182
	v_cmp_lt_i32_e32 vcc, v76, v201
	s_mov_b32 s0, 0x27ffffc
	v_and_b32_e32 v77, 48, v197
	v_cndmask_b32_e32 v76, v182, v76, vcc
	v_lshlrev_b32_e32 v118, 2, v76
	s_waitcnt lgkmcnt(0)
	v_pk_add_f32 v[72:73], v[72:73], v[74:75]
	ds_bpermute_b32 v75, v118, v73
	ds_bpermute_b32 v74, v118, v72
	v_xor_b32_e32 v76, 4, v182
	v_cmp_lt_i32_e32 vcc, v76, v201
	v_add_u32_e32 v92, 0, v197
	s_add_i32 s25, 0, 0x20500
	v_cndmask_b32_e32 v76, v182, v76, vcc
	v_lshlrev_b32_e32 v119, 2, v76
	s_waitcnt lgkmcnt(0)
	v_pk_add_f32 v[72:73], v[72:73], v[74:75]
	ds_bpermute_b32 v75, v119, v73
	ds_bpermute_b32 v74, v119, v72
	v_xor_b32_e32 v76, 8, v182
	v_cmp_lt_i32_e32 vcc, v76, v201
	global_load_dwordx4 v[28:31], v[14:15], off
	s_nop 0
	global_load_dwordx4 v[12:15], v[12:13], off offset:16
	v_cndmask_b32_e32 v76, v182, v76, vcc
	v_lshlrev_b32_e32 v120, 2, v76
	s_waitcnt lgkmcnt(0)
	v_pk_add_f32 v[72:73], v[72:73], v[74:75]
	ds_bpermute_b32 v75, v120, v73
	ds_bpermute_b32 v74, v120, v72
	v_and_or_b32 v76, v198, s0, v200
	v_lshl_or_b32 v121, v76, 6, v77
	v_mad_u64_u32 v[76:77], s[0:1], v183, s54, v[92:93]
	s_waitcnt lgkmcnt(0)
	v_pk_add_f32 v[72:73], v[72:73], v[74:75]
	global_load_dwordx4 v[32:35], v[18:19], off
	s_nop 0
	global_load_dwordx4 v[16:19], v[16:17], off offset:16
	v_pk_add_f32 v[86:87], v[72:73], s[4:5] op_sel_hi:[1,0]
	global_load_dwordx4 v[36:39], v[20:21], off
	s_nop 0
	global_load_dwordx4 v[20:23], v[22:23], off offset:16
	v_mul_f32_e32 v72, 0x4b800000, v87
	v_cmp_gt_f32_e32 vcc, s51, v87
	v_lshl_add_u32 v77, v183, 2, s25
	s_add_u32 s0, s10, s16
	v_cndmask_b32_e32 v72, v87, v72, vcc
	v_rsq_f32_e32 v72, v72
	v_mul_f32_e32 v87, 0x4b800000, v86
	s_addc_u32 s1, s11, s17
	v_lshlrev_b32_e32 v100, 16, v194
	v_mul_f32_e32 v73, 0x45800000, v72
	v_cndmask_b32_e32 v72, v72, v73, vcc
	v_mul_f32_e32 v72, 0x3db504f3, v72
	v_pk_mul_f32 v[90:91], v[90:91], v[72:73] op_sel_hi:[1,0]
	v_pk_mul_f32 v[94:95], v[110:111], v[72:73] op_sel_hi:[1,0]
	v_pk_mul_f32 v[96:97], v[106:107], v[72:73] op_sel_hi:[1,0]
	v_pk_mul_f32 v[2:3], v[2:3], v[72:73] op_sel_hi:[1,0]
	v_cvt_pk_bf16_f32 v72, v90, v91
	v_cvt_pk_bf16_f32 v73, v94, v95
	v_cvt_pk_bf16_f32 v74, v96, v97
	v_cvt_pk_bf16_f32 v75, v2, v3
	ds_write_b128 v76, v[72:75] offset:17408
	ds_read_b32 v74, v77
	v_cmp_gt_f32_e32 vcc, s51, v86
	v_and_or_b32 v72, v181, 14, v121
	v_lshlrev_b32_e32 v72, 3, v72
	v_cndmask_b32_e32 v86, v86, v87, vcc
	s_waitcnt lgkmcnt(0)
	v_mul_f32_e32 v74, 0x3fb8aa3b, v74
	v_exp_f32_e32 v98, v74
	v_rsq_f32_e32 v86, v86
	v_ashrrev_i32_e32 v73, 31, v72
	v_lshl_add_u64 v[78:79], v[72:73], 1, s[0:1]
	v_pk_mul_f32 v[72:73], v[98:99], v[90:91] op_sel_hi:[0,1]
	v_pk_mul_f32 v[74:75], v[98:99], v[94:95] op_sel_hi:[0,1]
	v_cvt_pk_bf16_f32 v72, v72, v73
	v_cvt_pk_bf16_f32 v73, v74, v75
	v_pk_mul_f32 v[74:75], v[98:99], v[96:97] op_sel_hi:[0,1]
	v_pk_mul_f32 v[2:3], v[98:99], v[2:3] op_sel_hi:[0,1]
	v_cvt_pk_bf16_f32 v74, v74, v75
	v_cvt_pk_bf16_f32 v75, v2, v3
	v_mul_f32_e32 v2, 0x45800000, v86
	v_cndmask_b32_e32 v2, v86, v2, vcc
	v_mul_f32_e32 v2, 0x3db504f3, v2
	v_pk_mul_f32 v[86:87], v[84:85], v[2:3] op_sel_hi:[1,0]
	v_pk_mul_f32 v[84:85], v[80:81], v[2:3] op_sel_hi:[1,0]
	v_pk_mul_f32 v[82:83], v[82:83], v[2:3] op_sel_hi:[1,0]
	v_pk_mul_f32 v[80:81], v[88:89], v[2:3] op_sel_hi:[1,0]
	v_lshlrev_b32_e32 v2, 16, v192
	v_and_b32_e32 v3, 0xffff0000, v192
	v_lshlrev_b32_e32 v98, 16, v193
	v_and_b32_e32 v99, 0xffff0000, v193
	v_pk_fma_f32 v[2:3], v[58:59], v[2:3], 0 op_sel_hi:[1,1,0]
	v_and_b32_e32 v101, 0xffff0000, v194
	s_waitcnt vmcnt(11)
	v_pk_fma_f32 v[2:3], v[66:67], v[98:99], v[2:3]
	v_lshlrev_b32_e32 v102, 16, v195
	v_and_b32_e32 v103, 0xffff0000, v195
	s_waitcnt vmcnt(10)
	v_pk_fma_f32 v[2:3], v[70:71], v[100:101], v[2:3]
	v_or_b32_e32 v77, 1, v181
	s_waitcnt vmcnt(8)
	v_pk_fma_f32 v[94:95], v[62:63], v[102:103], v[2:3]
	v_cvt_pk_bf16_f32 v88, v86, v87
	v_mul_f32_e32 v2, 0xbfb8aa3b, v95
	v_exp_f32_e32 v97, v2
	v_mul_f32_e32 v2, 0xbfb8aa3b, v94
	v_exp_f32_e32 v96, v2
	v_mad_u64_u32 v[2:3], s[2:3], v77, s54, v[92:93]
	v_cvt_pk_bf16_f32 v89, v84, v85
	v_pk_add_f32 v[92:93], v[96:97], 1.0 op_sel_hi:[1,0]
	v_cvt_pk_bf16_f32 v90, v82, v83
	s_nop 0
	s_nop 0
	v_cvt_pk_bf16_f32 v91, v80, v81
	ds_write_b128 v2, v[88:91] offset:17408
	s_nop 0
	s_nop 0
	s_nop 0
	s_nop 0
	s_nop 0
	s_nop 0
	s_nop 0
	s_nop 0
	s_nop 0
	s_nop 0
	v_rcp_f32_e32 v89, v93
	s_nop 0
	s_nop 0
	s_nop 0
	s_nop 0
	s_nop 0
	s_nop 0
	v_lshlrev_b32_e32 v90, 16, v188
	v_and_b32_e32 v91, 0xffff0000, v188
	v_lshlrev_b32_e32 v106, 16, v189
	v_and_b32_e32 v107, 0xffff0000, v189
	v_pk_fma_f32 v[90:91], v[56:57], v[90:91], 0 op_sel_hi:[1,1,0]
	v_lshlrev_b32_e32 v108, 16, v190
	v_and_b32_e32 v109, 0xffff0000, v190
	v_pk_fma_f32 v[90:91], v[64:65], v[106:107], v[90:91]
	v_lshlrev_b32_e32 v110, 16, v191
	v_and_b32_e32 v111, 0xffff0000, v191
	v_pk_fma_f32 v[90:91], v[68:69], v[108:109], v[90:91]
	s_nop 0
	v_pk_fma_f32 v[96:97], v[60:61], v[110:111], v[90:91]
	s_nop 0
	v_mul_f32_e32 v90, 0xbfb8aa3b, v96
	v_mul_f32_e32 v91, 0xbfb8aa3b, v97
	v_exp_f32_e32 v90, v90
	v_exp_f32_e32 v91, v91
	v_rcp_f32_e32 v88, v92
	s_nop 0
	v_pk_mul_f32 v[88:89], v[94:95], v[88:89]
	v_and_b32_e32 v113, 0xffff0000, v185
	v_pk_add_f32 v[104:105], v[90:91], 1.0 op_sel_hi:[1,0]
	v_lshlrev_b32_e32 v114, 16, v186
	s_nop 0
	s_nop 0
	s_nop 0
	s_nop 0
	s_nop 0
	s_nop 0
	s_nop 0
	s_nop 0
	s_nop 0
	s_nop 0
	s_nop 0
	s_nop 0
	v_rcp_f32_e32 v93, v105
	s_nop 0
	s_nop 0
	s_nop 0
	s_nop 0
	s_nop 0
	s_nop 0
	v_lshlrev_b32_e32 v94, 16, v184
	v_and_b32_e32 v95, 0xffff0000, v184
	v_lshlrev_b32_e32 v112, 16, v185
	v_pk_fma_f32 v[94:95], v[42:43], v[94:95], 0 op_sel_hi:[1,1,0]
	v_and_b32_e32 v115, 0xffff0000, v186
	v_pk_fma_f32 v[94:95], v[46:47], v[112:113], v[94:95]
	v_lshlrev_b32_e32 v116, 16, v187
	v_and_b32_e32 v117, 0xffff0000, v187
	v_pk_fma_f32 v[94:95], v[50:51], v[114:115], v[94:95]
	s_nop 0
	v_pk_fma_f32 v[122:123], v[54:55], v[116:117], v[94:95]
	s_nop 0
	v_mul_f32_e32 v94, 0xbfb8aa3b, v122
	v_mul_f32_e32 v95, 0xbfb8aa3b, v123
	v_exp_f32_e32 v94, v94
	v_exp_f32_e32 v95, v95
	v_rcp_f32_e32 v92, v104
	s_nop 0
	v_pk_mul_f32 v[92:93], v[96:97], v[92:93]
	v_and_b32_e32 v127, 0xffff0000, v178
	v_pk_add_f32 v[124:125], v[94:95], 1.0 op_sel_hi:[1,0]
	v_lshlrev_b32_e32 v128, 16, v179
	s_nop 0
	s_nop 0
	s_nop 0
	s_nop 0
	s_nop 0
	s_nop 0
	s_nop 0
	s_nop 0
	s_nop 0
	s_nop 0
	s_nop 0
	s_nop 0
	v_rcp_f32_e32 v97, v125
	s_nop 0
	s_nop 0
	s_nop 0
	s_nop 0
	s_nop 0
	s_nop 0
	v_lshlrev_b32_e32 v104, 16, v177
	v_and_b32_e32 v105, 0xffff0000, v177
	v_lshlrev_b32_e32 v126, 16, v178
	v_pk_fma_f32 v[104:105], v[40:41], v[104:105], 0 op_sel_hi:[1,1,0]
	v_and_b32_e32 v129, 0xffff0000, v179
	v_pk_fma_f32 v[104:105], v[44:45], v[126:127], v[104:105]
	v_lshlrev_b32_e32 v130, 16, v180
	v_and_b32_e32 v131, 0xffff0000, v180
	v_pk_fma_f32 v[104:105], v[48:49], v[128:129], v[104:105]
	s_nop 0
	v_pk_fma_f32 v[132:133], v[52:53], v[130:131], v[104:105]
	s_nop 0
	v_mul_f32_e32 v104, 0xbfb8aa3b, v132
	v_mul_f32_e32 v105, 0xbfb8aa3b, v133
	v_exp_f32_e32 v104, v104
	v_exp_f32_e32 v105, v105
	v_rcp_f32_e32 v96, v124
	s_nop 0
	v_pk_mul_f32 v[96:97], v[122:123], v[96:97]
	v_pk_fma_f32 v[58:59], v[58:59], v[98:99], 0 op_sel_hi:[1,1,0]
	v_pk_add_f32 v[160:161], v[104:105], 1.0 op_sel_hi:[1,0]
	v_pk_fma_f32 v[58:59], v[66:67], v[100:101], v[58:59]
	s_nop 0
	s_nop 0
	v_pk_fma_f32 v[58:59], v[70:71], v[102:103], v[58:59]
	v_lshlrev_b32_e32 v66, 16, v176
	v_and_b32_e32 v67, 0xffff0000, v176
	s_nop 0
	s_nop 0
	s_nop 0
	s_nop 0
	s_nop 0
	s_nop 0
	s_nop 0
	s_nop 0
	s_nop 0
	s_nop 0
	v_pk_fma_f32 v[62:63], v[62:63], v[66:67], v[58:59]
	v_rcp_f32_e32 v123, v161
	s_nop 0
	v_mul_f32_e32 v58, 0xbfb8aa3b, v63
	s_nop 0
	s_nop 0
	v_exp_f32_e32 v59, v58
	v_mul_f32_e32 v58, 0xbfb8aa3b, v62
	s_nop 0
	v_exp_f32_e32 v58, v58
	s_nop 0
	s_nop 0
	s_nop 0
	s_nop 0
	v_pk_add_f32 v[66:67], v[58:59], 1.0 op_sel_hi:[1,0]
	v_pk_fma_f32 v[56:57], v[56:57], v[106:107], 0 op_sel_hi:[1,1,0]
	s_nop 0
	s_nop 0
	v_pk_fma_f32 v[56:57], v[64:65], v[108:109], v[56:57]
	v_lshlrev_b32_e32 v64, 16, v175
	v_pk_fma_f32 v[56:57], v[68:69], v[110:111], v[56:57]
	s_nop 0
	s_nop 0
	s_nop 0
	s_nop 0
	s_nop 0
	s_nop 0
	s_nop 0
	s_nop 0
	s_nop 0
	s_nop 0
	v_and_b32_e32 v65, 0xffff0000, v175
	v_rcp_f32_e32 v67, v67
	s_nop 0
	v_pk_fma_f32 v[60:61], v[60:61], v[64:65], v[56:57]
	s_nop 0
	s_nop 0
	v_mul_f32_e32 v56, 0xbfb8aa3b, v60
	v_mul_f32_e32 v57, 0xbfb8aa3b, v61
	s_nop 0
	v_exp_f32_e32 v56, v56
	v_exp_f32_e32 v57, v57
	s_nop 0
	s_nop 0
	s_nop 0
	s_nop 0
	v_pk_add_f32 v[64:65], v[56:57], 1.0 op_sel_hi:[1,0]
	v_rcp_f32_e32 v66, v66
	s_nop 0
	s_nop 0
	v_pk_mul_f32 v[56:57], v[62:63], v[66:67]
	v_pk_fma_f32 v[42:43], v[42:43], v[112:113], 0 op_sel_hi:[1,1,0]
	v_pk_fma_f32 v[40:41], v[40:41], v[126:127], 0 op_sel_hi:[1,1,0]
	s_nop 0
	s_nop 0
	s_nop 0
	s_nop 0
	s_nop 0
	s_nop 0
	s_nop 0
	s_nop 0
	s_nop 0
	v_pk_fma_f32 v[42:43], v[46:47], v[114:115], v[42:43]
	v_lshlrev_b32_e32 v46, 16, v174
	v_pk_fma_f32 v[42:43], v[50:51], v[116:117], v[42:43]
	v_and_b32_e32 v47, 0xffff0000, v174
	v_pk_fma_f32 v[42:43], v[54:55], v[46:47], v[42:43]
	s_nop 0
	v_mul_f32_e32 v46, 0xbfb8aa3b, v42
	v_mul_f32_e32 v47, 0xbfb8aa3b, v43
	v_rcp_f32_e32 v65, v65
	s_nop 0
	v_exp_f32_e32 v46, v46
	v_exp_f32_e32 v47, v47
	s_nop 0
	s_nop 0
	s_nop 0
	s_nop 0
	s_nop 0
	v_pk_add_f32 v[46:47], v[46:47], 1.0 op_sel_hi:[1,0]
	s_nop 0
	s_nop 0
	s_nop 0
	s_nop 0
	v_rcp_f32_e32 v64, v64
	s_nop 0
	v_pk_mul_f32 v[50:51], v[60:61], v[64:65]
	v_pk_fma_f32 v[40:41], v[44:45], v[128:129], v[40:41]
	s_nop 0
	s_nop 0
	s_nop 0
	s_nop 0
	s_nop 0
	v_pk_fma_f32 v[40:41], v[48:49], v[130:131], v[40:41]
	v_lshlrev_b32_e32 v44, 16, v172
	v_and_b32_e32 v45, 0xffff0000, v172
	s_nop 0
	s_nop 0
	v_pk_fma_f32 v[40:41], v[52:53], v[44:45], v[40:41]
	s_nop 0
	v_mul_f32_e32 v44, 0xbfb8aa3b, v40
	v_mul_f32_e32 v45, 0xbfb8aa3b, v41
	v_exp_f32_e32 v44, v44
	v_exp_f32_e32 v45, v45
	s_nop 0
	s_nop 0
	v_rcp_f32_e32 v47, v47
	s_nop 0
	s_nop 0
	s_nop 0
	v_pk_add_f32 v[44:45], v[44:45], 1.0 op_sel_hi:[1,0]
	s_nop 0
	s_nop 0
	s_nop 0
	s_nop 0
	s_nop 0
	s_nop 0
	s_nop 0
	v_rcp_f32_e32 v46, v46
	s_nop 0
	s_nop 0
	s_nop 0
	s_nop 0
	s_nop 0
	s_nop 0
	s_nop 0
	s_nop 0
	s_nop 0
	s_nop 0
	v_rcp_f32_e32 v45, v45
	v_rcp_f32_e32 v122, v160
	s_nop 0
	s_nop 0
	s_nop 0
	s_nop 0
	s_nop 0
	s_nop 0
	s_nop 0
	s_nop 0
	v_rcp_f32_e32 v44, v44
	v_pk_mul_f32 v[58:59], v[132:133], v[122:123]
	v_pk_mul_f32 v[44:45], v[40:41], v[44:45]
	v_pk_mul_f32 v[70:71], v[58:59], v[58:59]
	v_pk_mul_f32 v[46:47], v[42:43], v[46:47]
	v_pk_mul_f32 v[40:41], v[44:45], v[44:45]
	v_pk_mul_f32 v[104:105], v[96:97], v[96:97]
	v_pk_mul_f32 v[42:43], v[46:47], v[46:47]
	v_mov_b32_e32 v48, v40
	v_mov_b32_e32 v49, v70
	v_mov_b32_e32 v70, v41
	v_pk_add_f32 v[40:41], v[48:49], v[70:71]
	v_mov_b32_e32 v48, v42
	v_mov_b32_e32 v49, v104
	v_pk_mul_f32 v[94:95], v[92:93], v[92:93]
	v_pk_mul_f32 v[54:55], v[50:51], v[50:51]
	v_pk_add_f32 v[40:41], v[48:49], v[40:41]
	v_mov_b32_e32 v104, v43
	v_pk_add_f32 v[40:41], v[104:105], v[40:41]
	v_mov_b32_e32 v42, v54
	v_mov_b32_e32 v43, v94
	v_pk_mul_f32 v[90:91], v[88:89], v[88:89]
	v_pk_mul_f32 v[62:63], v[56:57], v[56:57]
	v_pk_add_f32 v[40:41], v[42:43], v[40:41]
	v_mov_b32_e32 v94, v55
	v_pk_add_f32 v[40:41], v[94:95], v[40:41]
	v_mov_b32_e32 v42, v62
	v_mov_b32_e32 v43, v90
	v_pk_add_f32 v[40:41], v[42:43], v[40:41]
	v_mov_b32_e32 v90, v63
	v_pk_add_f32 v[40:41], v[90:91], v[40:41]
	v_lshl_add_u32 v3, v77, 2, s25
	ds_bpermute_b32 v43, v173, v41
	ds_bpermute_b32 v42, v173, v40
	ds_read_b32 v3, v3
	s_mov_b32 s2, 0x13800000
	v_add_co_u32_e32 v48, vcc, s2, v78
	s_waitcnt lgkmcnt(1)
	v_pk_add_f32 v[42:43], v[40:41], v[42:43]
	v_addc_co_u32_e32 v49, vcc, 0, v79, vcc
	s_waitcnt lgkmcnt(0)
	v_mul_f32_e32 v3, 0x3fb8aa3b, v3
	ds_bpermute_b32 v53, v118, v43
	ds_bpermute_b32 v52, v118, v42
	global_store_dwordx4 v[48:49], v[72:75], off nt
	v_exp_f32_e32 v48, v3
	v_and_or_b32 v3, v77, 15, v121
	v_lshlrev_b32_e32 v66, 16, v144
	s_waitcnt lgkmcnt(0)
	v_pk_add_f32 v[52:53], v[42:43], v[52:53]
	v_pk_mul_f32 v[40:41], v[48:49], v[86:87] op_sel_hi:[0,1]
	v_pk_mul_f32 v[54:55], v[48:49], v[84:85] op_sel_hi:[0,1]
	v_cvt_pk_bf16_f32 v40, v40, v41
	v_cvt_pk_bf16_f32 v41, v54, v55
	ds_bpermute_b32 v55, v119, v53
	ds_bpermute_b32 v54, v119, v52
	v_pk_mul_f32 v[42:43], v[48:49], v[82:83] op_sel_hi:[0,1]
	v_pk_mul_f32 v[48:49], v[48:49], v[80:81] op_sel_hi:[0,1]
	v_cvt_pk_bf16_f32 v42, v42, v43
	v_cvt_pk_bf16_f32 v43, v48, v49
	s_waitcnt lgkmcnt(0)
	v_pk_add_f32 v[48:49], v[52:53], v[54:55]
	ds_bpermute_b32 v53, v120, v49
	ds_bpermute_b32 v52, v120, v48
	v_lshlrev_b32_e32 v54, 3, v3
	v_ashrrev_i32_e32 v55, 31, v54
	v_lshl_add_u64 v[54:55], v[54:55], 1, s[0:1]
	v_and_b32_e32 v67, 0xffff0000, v144
	s_waitcnt lgkmcnt(0)
	v_pk_add_f32 v[48:49], v[48:49], v[52:53]
	v_add_co_u32_e64 v52, s[0:1], s2, v54
	v_pk_add_f32 v[48:49], v[48:49], s[4:5] op_sel_hi:[1,0]
	s_nop 0
	v_addc_co_u32_e64 v53, s[0:1], 0, v55, s[0:1]
	v_mul_f32_e32 v3, 0x4b800000, v49
	v_cmp_gt_f32_e32 vcc, s51, v49
	global_store_dwordx4 v[52:53], v[40:43], off nt
	s_waitcnt vmcnt(9)
	v_pk_fma_f32 v[66:67], v[8:9], v[66:67], 0 op_sel_hi:[1,1,0]
	v_cndmask_b32_e32 v3, v49, v3, vcc
	v_rsq_f32_e32 v3, v3
	v_and_b32_e32 v73, 0xffff0000, v140
	s_bfe_u32 s28, s24, 0x20006
	s_ashr_i32 s26, s24, 7
	v_mul_f32_e32 v40, 0x45800000, v3
	v_cndmask_b32_e32 v40, v3, v40, vcc
	v_mul_f32_e32 v3, 0x4b800000, v48
	v_cmp_gt_f32_e32 vcc, s51, v48
	v_pk_mul_f32 v[42:43], v[58:59], v[40:41] op_sel_hi:[1,0]
	v_pk_mul_f32 v[52:53], v[96:97], v[40:41] op_sel_hi:[1,0]
	v_cndmask_b32_e32 v3, v48, v3, vcc
	v_rsq_f32_e32 v3, v3
	v_pk_mul_f32 v[54:55], v[92:93], v[40:41] op_sel_hi:[1,0]
	v_pk_mul_f32 v[58:59], v[88:89], v[40:41] op_sel_hi:[1,0]
	v_cvt_pk_bf16_f32 v40, v42, v43
	v_cvt_pk_bf16_f32 v41, v52, v53
	v_cvt_pk_bf16_f32 v42, v54, v55
	v_cvt_pk_bf16_f32 v43, v58, v59
	ds_write_b128 v76, v[40:43]
	v_mul_f32_e32 v40, 0x45800000, v3
	v_cndmask_b32_e32 v48, v3, v40, vcc
	v_pk_mul_f32 v[54:55], v[46:47], v[48:49] op_sel_hi:[1,0]
	v_lshlrev_b32_e32 v46, 16, v168
	v_and_b32_e32 v47, 0xffff0000, v168
	v_lshlrev_b32_e32 v40, 16, v169
	v_and_b32_e32 v41, 0xffff0000, v169
	s_waitcnt vmcnt(8)
	v_pk_fma_f32 v[46:47], v[24:25], v[46:47], 0 op_sel_hi:[1,1,0]
	v_lshlrev_b32_e32 v42, 16, v170
	v_and_b32_e32 v43, 0xffff0000, v170
	s_waitcnt vmcnt(7)
	v_pk_fma_f32 v[46:47], v[28:29], v[40:41], v[46:47]
	v_pk_mul_f32 v[52:53], v[44:45], v[48:49] op_sel_hi:[1,0]
	v_lshlrev_b32_e32 v44, 16, v171
	v_and_b32_e32 v45, 0xffff0000, v171
	s_waitcnt vmcnt(5)
	v_pk_fma_f32 v[46:47], v[32:33], v[42:43], v[46:47]
	v_pk_mul_f32 v[50:51], v[50:51], v[48:49] op_sel_hi:[1,0]
	s_waitcnt vmcnt(3)
	v_pk_fma_f32 v[58:59], v[36:37], v[44:45], v[46:47]
	v_cvt_pk_bf16_f32 v46, v52, v53
	v_mul_f32_e32 v3, 0xbfb8aa3b, v58
	v_exp_f32_e32 v60, v3
	v_mul_f32_e32 v3, 0xbfb8aa3b, v59
	v_exp_f32_e32 v61, v3
	v_cvt_pk_bf16_f32 v47, v54, v55
	v_pk_mul_f32 v[56:57], v[56:57], v[48:49] op_sel_hi:[1,0]
	v_cvt_pk_bf16_f32 v48, v50, v51
	v_pk_add_f32 v[52:53], v[60:61], 1.0 op_sel_hi:[1,0]
	v_cvt_pk_bf16_f32 v49, v56, v57
	s_nop 0
	s_nop 0
	ds_write_b128 v2, v[46:49]
	v_and_b32_e32 v55, 0xffff0000, v148
	s_nop 0
	s_nop 0
	s_nop 0
	s_nop 0
	s_nop 0
	s_nop 0
	s_nop 0
	s_nop 0
	s_nop 0
	v_lshlrev_b32_e32 v54, 16, v148
	v_lshlrev_b32_e32 v46, 16, v149
	v_and_b32_e32 v47, 0xffff0000, v149
	v_pk_fma_f32 v[54:55], v[26:27], v[54:55], 0 op_sel_hi:[1,1,0]
	s_nop 0
	v_lshlrev_b32_e32 v48, 16, v150
	v_and_b32_e32 v49, 0xffff0000, v150
	v_pk_fma_f32 v[54:55], v[30:31], v[46:47], v[54:55]
	v_lshlrev_b32_e32 v50, 16, v151
	v_and_b32_e32 v51, 0xffff0000, v151
	v_pk_fma_f32 v[54:55], v[34:35], v[48:49], v[54:55]
	v_rcp_f32_e32 v53, v53
	v_pk_fma_f32 v[60:61], v[38:39], v[50:51], v[54:55]
	s_nop 0
	v_mul_f32_e32 v54, 0xbfb8aa3b, v60
	v_mul_f32_e32 v55, 0xbfb8aa3b, v61
	v_exp_f32_e32 v54, v54
	v_exp_f32_e32 v55, v55
	s_nop 0
	s_nop 0
	s_nop 0
	s_nop 0
	s_nop 0
	v_pk_add_f32 v[62:63], v[54:55], 1.0 op_sel_hi:[1,0]
	s_nop 0
	s_nop 0
	s_nop 0
	s_nop 0
	v_rcp_f32_e32 v52, v52
	s_nop 0
	v_pk_mul_f32 v[64:65], v[58:59], v[52:53]
	s_nop 0
	s_nop 0
	s_nop 0
	s_nop 0
	s_nop 0
	s_nop 0
	s_nop 0
	s_nop 0
	v_lshlrev_b32_e32 v52, 16, v145
	v_and_b32_e32 v53, 0xffff0000, v145
	s_nop 0
	v_lshlrev_b32_e32 v54, 16, v146
	v_and_b32_e32 v55, 0xffff0000, v146
	v_pk_fma_f32 v[66:67], v[12:13], v[52:53], v[66:67]
	s_nop 0
	v_lshlrev_b32_e32 v56, 16, v147
	v_and_b32_e32 v57, 0xffff0000, v147
	v_pk_fma_f32 v[66:67], v[16:17], v[54:55], v[66:67]
	v_rcp_f32_e32 v59, v63
	s_waitcnt vmcnt(2)
	v_pk_fma_f32 v[66:67], v[20:21], v[56:57], v[66:67]
	s_nop 0
	v_mul_f32_e32 v68, 0xbfb8aa3b, v66
	v_mul_f32_e32 v69, 0xbfb8aa3b, v67
	v_exp_f32_e32 v68, v68
	v_exp_f32_e32 v69, v69
	s_nop 0
	s_nop 0
	s_nop 0
	s_nop 0
	v_pk_add_f32 v[68:69], v[68:69], 1.0 op_sel_hi:[1,0]
	s_nop 0
	s_nop 0
	s_nop 0
	s_nop 0
	s_nop 0
	v_rcp_f32_e32 v58, v62
	s_nop 0
	s_nop 0
	s_nop 0
	v_pk_mul_f32 v[62:63], v[60:61], v[58:59]
	s_nop 0
	s_nop 0
	s_nop 0
	s_nop 0
	s_nop 0
	v_lshlrev_b32_e32 v72, 16, v140
	v_lshlrev_b32_e32 v58, 16, v141
	v_and_b32_e32 v59, 0xffff0000, v141
	v_pk_fma_f32 v[72:73], v[10:11], v[72:73], 0 op_sel_hi:[1,1,0]
	s_nop 0
	v_lshlrev_b32_e32 v60, 16, v142
	v_and_b32_e32 v61, 0xffff0000, v142
	v_pk_fma_f32 v[72:73], v[14:15], v[58:59], v[72:73]
	s_nop 0
	v_lshlrev_b32_e32 v70, 16, v143
	v_and_b32_e32 v71, 0xffff0000, v143
	v_pk_fma_f32 v[72:73], v[18:19], v[60:61], v[72:73]
	v_rcp_f32_e32 v69, v69
	v_pk_fma_f32 v[72:73], v[22:23], v[70:71], v[72:73]
	s_nop 0
	v_mul_f32_e32 v74, 0xbfb8aa3b, v73
	v_exp_f32_e32 v75, v74
	v_mul_f32_e32 v74, 0xbfb8aa3b, v72
	v_exp_f32_e32 v74, v74
	s_nop 0
	s_nop 0
	s_nop 0
	s_nop 0
	s_nop 0
	v_pk_add_f32 v[74:75], v[74:75], 1.0 op_sel_hi:[1,0]
	s_nop 0
	s_nop 0
	s_nop 0
	s_nop 0
	v_rcp_f32_e32 v68, v68
	s_nop 0
	v_pk_mul_f32 v[66:67], v[66:67], v[68:69]
	s_nop 0
	s_nop 0
	s_nop 0
	s_nop 0
	s_nop 0
	s_nop 0
	s_nop 0
	s_nop 0
	s_nop 0
	s_nop 0
	v_rcp_f32_e32 v69, v75
	v_pk_fma_f32 v[24:25], v[24:25], v[40:41], 0 op_sel_hi:[1,1,0]
	s_nop 0
	s_nop 0
	s_nop 0
	s_nop 0
	s_nop 0
	s_nop 0
	v_pk_fma_f32 v[24:25], v[28:29], v[42:43], v[24:25]
	s_nop 0
	v_pk_fma_f32 v[24:25], v[32:33], v[44:45], v[24:25]
	v_lshlrev_b32_e32 v28, 16, v139
	v_and_b32_e32 v29, 0xffff0000, v139
	s_nop 0
	v_pk_fma_f32 v[24:25], v[36:37], v[28:29], v[24:25]
	v_rcp_f32_e32 v68, v74
	v_mul_f32_e32 v3, 0xbfb8aa3b, v24
	v_exp_f32_e32 v28, v3
	v_mul_f32_e32 v3, 0xbfb8aa3b, v25
	v_exp_f32_e32 v29, v3
	v_pk_mul_f32 v[32:33], v[72:73], v[68:69]
	v_pk_fma_f32 v[26:27], v[26:27], v[46:47], 0 op_sel_hi:[1,1,0]
	v_cvt_pk_bf16_f32 v43, v32, v33
	v_pk_add_f32 v[28:29], v[28:29], 1.0 op_sel_hi:[1,0]
	v_pk_fma_f32 v[26:27], v[30:31], v[48:49], v[26:27]
	s_nop 0
	s_nop 0
	v_pk_fma_f32 v[26:27], v[34:35], v[50:51], v[26:27]
	v_lshlrev_b32_e32 v30, 16, v138
	v_and_b32_e32 v31, 0xffff0000, v138
	s_nop 0
	s_nop 0
	s_nop 0
	s_nop 0
	s_nop 0
	s_nop 0
	s_nop 0
	s_nop 0
	s_nop 0
	v_pk_fma_f32 v[26:27], v[38:39], v[30:31], v[26:27]
	s_nop 0
	v_mul_f32_e32 v30, 0xbfb8aa3b, v26
	v_mul_f32_e32 v31, 0xbfb8aa3b, v27
	v_rcp_f32_e32 v29, v29
	s_nop 0
	v_exp_f32_e32 v30, v30
	v_exp_f32_e32 v31, v31
	s_nop 0
	s_nop 0
	s_nop 0
	s_nop 0
	s_nop 0
	v_pk_add_f32 v[30:31], v[30:31], 1.0 op_sel_hi:[1,0]
	s_nop 0
	s_nop 0
	s_nop 0
	s_nop 0
	v_rcp_f32_e32 v28, v28
	s_nop 0
	v_pk_mul_f32 v[24:25], v[24:25], v[28:29]
	s_nop 0
	s_nop 0
	s_nop 0
	s_nop 0
	v_pk_fma_f32 v[8:9], v[8:9], v[52:53], 0 op_sel_hi:[1,1,0]
	s_nop 0
	v_pk_fma_f32 v[8:9], v[12:13], v[54:55], v[8:9]
	s_nop 0
	v_pk_fma_f32 v[8:9], v[16:17], v[56:57], v[8:9]
	v_lshlrev_b32_e32 v12, 16, v137
	v_and_b32_e32 v13, 0xffff0000, v137
	s_nop 0
	s_nop 0
	v_pk_fma_f32 v[8:9], v[20:21], v[12:13], v[8:9]
	s_nop 0
	v_mul_f32_e32 v12, 0xbfb8aa3b, v8
	v_mul_f32_e32 v13, 0xbfb8aa3b, v9
	v_exp_f32_e32 v12, v12
	v_exp_f32_e32 v13, v13
	s_nop 0
	v_rcp_f32_e32 v29, v31
	s_nop 0
	s_nop 0
	s_nop 0
	v_pk_add_f32 v[12:13], v[12:13], 1.0 op_sel_hi:[1,0]
	s_nop 0
	s_nop 0
	s_nop 0
	s_nop 0
	s_nop 0
	s_nop 0
	s_nop 0
	v_rcp_f32_e32 v28, v30
	s_nop 0
	s_nop 0
	s_nop 0
	v_pk_mul_f32 v[16:17], v[26:27], v[28:29]
	s_nop 0
	s_nop 0
	v_pk_fma_f32 v[10:11], v[10:11], v[58:59], 0 op_sel_hi:[1,1,0]
	s_nop 0
	v_pk_fma_f32 v[10:11], v[14:15], v[60:61], v[10:11]
	s_nop 0
	s_nop 0
	v_pk_fma_f32 v[10:11], v[18:19], v[70:71], v[10:11]
	v_lshlrev_b32_e32 v14, 16, v136
	v_and_b32_e32 v15, 0xffff0000, v136
	s_nop 0
	v_pk_fma_f32 v[10:11], v[22:23], v[14:15], v[10:11]
	s_nop 0
	v_mul_f32_e32 v14, 0xbfb8aa3b, v11
	v_exp_f32_e32 v15, v14
	v_mul_f32_e32 v14, 0xbfb8aa3b, v10
	v_exp_f32_e32 v14, v14
	v_rcp_f32_e32 v13, v13
	s_nop 0
	s_nop 0
	s_nop 0
	s_nop 0
	s_nop 0
	v_pk_add_f32 v[14:15], v[14:15], 1.0 op_sel_hi:[1,0]
	s_nop 0
	s_nop 0
	s_nop 0
	s_nop 0
	s_nop 0
	v_rcp_f32_e32 v12, v12
	s_nop 0
	s_nop 0
	s_nop 0
	v_pk_mul_f32 v[12:13], v[8:9], v[12:13]
	s_nop 0
	s_nop 0
	s_nop 0
	s_nop 0
	s_nop 0
	s_nop 0
	s_nop 0
	v_rcp_f32_e32 v9, v15
	s_lshl_b32 s29, s28, 4
	s_nop 0
	s_nop 0
	s_nop 0
	s_nop 0
	s_nop 0
	s_nop 0
	s_nop 0
	s_nop 0
	v_rcp_f32_e32 v8, v14
	s_nop 0
	v_pk_mul_f32 v[14:15], v[10:11], v[8:9]
	v_cvt_pk_bf16_f32 v8, v24, v25
	v_cvt_pk_bf16_f32 v9, v16, v17
	v_cvt_pk_bf16_f32 v10, v12, v13
	v_cvt_pk_bf16_f32 v11, v14, v15
	v_and_b32_e32 v3, 48, v134
	ds_write_b128 v2, v[8:11] offset:34816
	s_and_b32 s27, s26, -2
	v_or_b32_e32 v2, s29, v1
	v_add_u32_e32 v48, 0, v3
	v_cvt_pk_bf16_f32 v40, v64, v65
	v_cvt_pk_bf16_f32 v41, v62, v63
	v_cvt_pk_bf16_f32 v42, v66, v67
	v_mad_u32_u24 v55, v2, s54, v48
	v_lshl_or_b32 v59, s27, 4, v1
	ds_write_b128 v76, v[40:43] offset:34816
	s_waitcnt lgkmcnt(0)
	s_barrier
	s_lshr_b32 s0, s24, 6
	s_and_b32 s1, s0, 3
	s_lshr_b32 s2, s0, 2
	s_lshl_b32 s2, s2, 1
	v_lshrrev_b32_e32 v3, 4, v134
	v_mul_u32_u24_e32 v4, 0x110, v1
	v_lshl_add_u32 v4, v3, 4, v4
	s_mul_i32 s3, s1, 0x1100
	s_mul_i32 s4, s2, 0x1100
	v_add_u32_e32 v2, s3, v4
	v_add_u32_e32 v4, s4, v4
	s_lshl_b32 s5, s1, 6
	s_add_u32 s5, s5, 0x20500
	v_lshl_add_u32 v5, v3, 4, s5
	s_lshl_b32 s6, s2, 6
	s_add_u32 s6, s6, 0x20500
	v_lshl_add_u32 v6, v1, 2, s6
	v_mul_u32_u24_e32 v7, 0x110, v1
	v_lshl_add_u32 v7, v3, 4, v7
	s_lshl_b32 s7, s1, 6
	s_add_u32 s7, s7, s4
	s_add_u32 s7, s7, 0xcc00
	v_add_u32_e32 v7, s7, v7
	v_mul_u32_u24_e32 v9, 0x240, v3
	v_lshl_add_u32 v9, v1, 1, v9
	s_mul_i32 s26, s1, 0x900
	s_lshl_b32 s27, s2, 5
	s_add_u32 s26, s26, s27
	s_add_u32 s26, s26, 0x11000
	v_add_u32_e32 v9, s26, v9
	v_lshrrev_b32_e32 v10, 1, v3
	v_lshlrev_b32_e32 v10, 8, v10
	v_lshl_add_u32 v10, v1, 4, v10
	v_and_b32_e32 v11, 1, v3
	v_lshl_add_u32 v10, v11, 3, v10
	s_lshl_b32 s27, s2, 11
	s_lshl_b32 s28, s1, 9
	s_add_u32 s27, s27, s28
	v_add_u32_e32 v10, s27, v10
	s_add_u32 s26, s10, s18
	s_addc_u32 s27, s11, s19
	s_lshl_b32 s28, s2, 4
	s_lshl_b32 s29, s1, 4
	s_sub_i32 s28, s28, s29
	v_lshlrev_b32_e32 v11, 2, v3
	v_sub_u32_e32 v11, v1, v11
	v_add_u32_e32 v11, s28, v11
	v_add_u32_e32 v70, 16, v11
	ds_read_b128 v[60:63], v5
	ds_read_b128 v[64:67], v5 offset:256
	ds_read_b32 v68, v6
	ds_read_b32 v69, v6 offset:64
	ds_read_b128 v[12:15], v2 offset:0
	ds_read_b128 v[28:31], v4 offset:0
	ds_read_b128 v[44:47], v4 offset:17408
	ds_read_b128 v[16:19], v2 offset:64
	ds_read_b128 v[32:35], v4 offset:64
	ds_read_b128 v[48:51], v4 offset:17472
	ds_read_b128 v[20:23], v2 offset:128
	ds_read_b128 v[36:39], v4 offset:128
	ds_read_b128 v[52:55], v4 offset:17536
	ds_read_b128 v[24:27], v2 offset:192
	ds_read_b128 v[40:43], v4 offset:192
	ds_read_b128 v[56:59], v4 offset:17600
	ds_read_b128 v[136:139], v4 offset:4352
	ds_read_b128 v[168:171], v4 offset:21760
	ds_read_b128 v[140:143], v4 offset:4416
	ds_read_b128 v[172:175], v4 offset:21824
	ds_read_b128 v[144:147], v4 offset:4480
	ds_read_b128 v[176:179], v4 offset:21888
	ds_read_b128 v[148:151], v4 offset:4544
	ds_read_b128 v[184:187], v4 offset:21952
	s_waitcnt lgkmcnt(14)
	v_mfma_f32_16x16x32_bf16 v[160:163], v[12:15], v[28:31], 0
	v_mfma_f32_16x16x32_bf16 v[200:203], v[12:15], v[44:47], 0
	s_waitcnt lgkmcnt(14)
	v_mfma_f32_16x16x32_bf16 v[160:163], v[16:19], v[32:35], v[160:163]
	v_mfma_f32_16x16x32_bf16 v[200:203], v[16:19], v[48:51], v[200:203]
	s_waitcnt lgkmcnt(11)
	v_mfma_f32_16x16x32_bf16 v[160:163], v[20:23], v[36:39], v[160:163]
	v_mfma_f32_16x16x32_bf16 v[200:203], v[20:23], v[52:55], v[200:203]
	s_waitcnt lgkmcnt(8)
	v_mfma_f32_16x16x32_bf16 v[160:163], v[24:27], v[40:43], v[160:163]
	v_mfma_f32_16x16x32_bf16 v[200:203], v[24:27], v[56:59], v[200:203]
	s_waitcnt lgkmcnt(6)
	v_mfma_f32_16x16x32_bf16 v[234:237], v[12:15], v[136:139], 0
	v_mfma_f32_16x16x32_bf16 v[238:241], v[12:15], v[168:171], 0
	s_waitcnt lgkmcnt(4)
	v_mfma_f32_16x16x32_bf16 v[234:237], v[16:19], v[140:143], v[234:237]
	v_mfma_f32_16x16x32_bf16 v[238:241], v[16:19], v[172:175], v[238:241]
	s_waitcnt lgkmcnt(2)
	v_mfma_f32_16x16x32_bf16 v[234:237], v[20:23], v[144:147], v[234:237]
	v_mfma_f32_16x16x32_bf16 v[238:241], v[20:23], v[176:179], v[238:241]
	s_waitcnt lgkmcnt(0)
	v_mfma_f32_16x16x32_bf16 v[234:237], v[24:27], v[148:151], v[234:237]
	v_mfma_f32_16x16x32_bf16 v[238:241], v[24:27], v[184:187], v[238:241]
	v_cmp_lt_i32_e64 s[0:1], v11, 0
	v_cmp_lt_i32_e64 s[2:3], v11, 1
	v_cmp_lt_i32_e64 s[4:5], v11, 2
	v_cmp_lt_i32_e64 s[6:7], v11, 3
	v_cmp_lt_i32_e64 s[28:29], v70, 0
	v_cmp_lt_i32_e64 s[30:31], v70, 1
	v_cmp_lt_i32_e64 s[32:33], v70, 2
	v_cmp_lt_i32_e64 s[34:35], v70, 3
	v_sub_f32_e32 v70, v60, v68
	v_sub_f32_e32 v164, v68, v60
	v_sub_f32_e32 v71, v61, v68
	v_sub_f32_e32 v165, v68, v61
	v_sub_f32_e32 v72, v62, v68
	v_sub_f32_e32 v180, v68, v62
	v_sub_f32_e32 v73, v63, v68
	v_sub_f32_e32 v181, v68, v63
	v_mul_f32_e32 v70, 0x3fb8aa3b, v70
	v_mul_f32_e32 v164, 0x3fb8aa3b, v164
	v_mul_f32_e32 v71, 0x3fb8aa3b, v71
	v_mul_f32_e32 v165, 0x3fb8aa3b, v165
	v_mul_f32_e32 v72, 0x3fb8aa3b, v72
	v_mul_f32_e32 v180, 0x3fb8aa3b, v180
	v_mul_f32_e32 v73, 0x3fb8aa3b, v73
	v_mul_f32_e32 v181, 0x3fb8aa3b, v181
	v_exp_f32_e32 v70, v70
	v_exp_f32_e32 v164, v164
	v_exp_f32_e32 v71, v71
	v_exp_f32_e32 v165, v165
	v_exp_f32_e32 v72, v72
	v_exp_f32_e32 v180, v180
	v_exp_f32_e32 v73, v73
	v_exp_f32_e32 v181, v181
	v_mul_f32_e32 v160, v160, v70
	v_mul_f32_e32 v200, v200, v164
	v_mul_f32_e32 v161, v161, v71
	v_mul_f32_e32 v201, v201, v165
	v_mul_f32_e32 v162, v162, v72
	v_mul_f32_e32 v202, v202, v180
	v_mul_f32_e32 v163, v163, v73
	v_mul_f32_e32 v203, v203, v181
	v_mul_f32_e32 v160, v64, v160
	v_mul_f32_e32 v161, v65, v161
	v_mul_f32_e32 v162, v66, v162
	v_mul_f32_e32 v163, v67, v163
	v_cndmask_b32_e64 v160, 0, v160, s[0:1]
	v_cndmask_b32_e64 v200, v200, 0, s[0:1]
	v_cndmask_b32_e64 v161, 0, v161, s[2:3]
	v_cndmask_b32_e64 v201, v201, 0, s[2:3]
	v_cndmask_b32_e64 v162, 0, v162, s[4:5]
	v_cndmask_b32_e64 v202, v202, 0, s[4:5]
	v_cndmask_b32_e64 v163, 0, v163, s[6:7]
	v_cndmask_b32_e64 v203, v203, 0, s[6:7]
	ds_write_b128 v7, v[160:163]
	v_cvt_pk_bf16_f32 v204, v160, v161
	v_cvt_pk_bf16_f32 v205, v162, v163
	ds_write_b16 v9, v204
	ds_write_b16_d16_hi v9, v204 offset:144
	ds_write_b16 v9, v205 offset:288
	ds_write_b16_d16_hi v9, v205 offset:432
	v_cvt_pk_bf16_f32 v200, v200, v201
	v_cvt_pk_bf16_f32 v201, v202, v203
	global_store_dwordx2 v10, v[200:201], s[26:27] nt
	v_sub_f32_e32 v70, v60, v69
	v_sub_f32_e32 v164, v69, v60
	v_sub_f32_e32 v71, v61, v69
	v_sub_f32_e32 v165, v69, v61
	v_sub_f32_e32 v72, v62, v69
	v_sub_f32_e32 v180, v69, v62
	v_sub_f32_e32 v73, v63, v69
	v_sub_f32_e32 v181, v69, v63
	v_mul_f32_e32 v70, 0x3fb8aa3b, v70
	v_mul_f32_e32 v164, 0x3fb8aa3b, v164
	v_mul_f32_e32 v71, 0x3fb8aa3b, v71
	v_mul_f32_e32 v165, 0x3fb8aa3b, v165
	v_mul_f32_e32 v72, 0x3fb8aa3b, v72
	v_mul_f32_e32 v180, 0x3fb8aa3b, v180
	v_mul_f32_e32 v73, 0x3fb8aa3b, v73
	v_mul_f32_e32 v181, 0x3fb8aa3b, v181
	v_exp_f32_e32 v70, v70
	v_exp_f32_e32 v164, v164
	v_exp_f32_e32 v71, v71
	v_exp_f32_e32 v165, v165
	v_exp_f32_e32 v72, v72
	v_exp_f32_e32 v180, v180
	v_exp_f32_e32 v73, v73
	v_exp_f32_e32 v181, v181
	v_mul_f32_e32 v234, v234, v70
	v_mul_f32_e32 v238, v238, v164
	v_mul_f32_e32 v235, v235, v71
	v_mul_f32_e32 v239, v239, v165
	v_mul_f32_e32 v236, v236, v72
	v_mul_f32_e32 v240, v240, v180
	v_mul_f32_e32 v237, v237, v73
	v_mul_f32_e32 v241, v241, v181
	v_mul_f32_e32 v234, v64, v234
	v_mul_f32_e32 v235, v65, v235
	v_mul_f32_e32 v236, v66, v236
	v_mul_f32_e32 v237, v67, v237
	v_cndmask_b32_e64 v234, 0, v234, s[28:29]
	v_cndmask_b32_e64 v238, v238, 0, s[28:29]
	v_cndmask_b32_e64 v235, 0, v235, s[30:31]
	v_cndmask_b32_e64 v239, v239, 0, s[30:31]
	v_cndmask_b32_e64 v236, 0, v236, s[32:33]
	v_cndmask_b32_e64 v240, v240, 0, s[32:33]
	v_cndmask_b32_e64 v237, 0, v237, s[34:35]
	v_cndmask_b32_e64 v241, v241, 0, s[34:35]
	ds_write_b128 v7, v[234:237] offset:4352
	v_cvt_pk_bf16_f32 v246, v234, v235
	v_cvt_pk_bf16_f32 v247, v236, v237
	ds_write_b16 v9, v246 offset:32
	ds_write_b16_d16_hi v9, v246 offset:176
	ds_write_b16 v9, v247 offset:320
	ds_write_b16_d16_hi v9, v247 offset:464
	v_cvt_pk_bf16_f32 v238, v238, v239
	v_cvt_pk_bf16_f32 v239, v240, v241
	global_store_dwordx2 v10, v[238:239], s[26:27] offset:2048 nt
	s_waitcnt lgkmcnt(0)
	s_barrier
	v_readfirstlane_b32 s26, v135
	s_lshr_b32 s26, s26, 6
	s_cmp_eq_u32 s26, 0
	s_cbranch_scc1 .Lpd_inv
	s_cmp_lt_u32 s26, 4
	s_cbranch_scc1 .Lpd_done
	s_lshr_b32 s27, s26, 1
	s_and_b32 s27, s27, 1
	s_and_b32 s28, s26, 1
	s_lshl_b32 s28, s28, 6
	v_and_b32_e32 v4, 63, v135
	v_add_u32_e32 v5, s28, v4
	s_mul_i32 s29, s27, 0x2200
	v_lshl_add_u32 v6, v5, 1, s29
	s_lshl_b32 s30, s27, 7
	s_add_u32 s30, s30, s25
	v_and_b32_e32 v7, 31, v135
	v_lshl_add_u32 v7, v7, 2, s30
	v_mov_b32_e32 v9, s25
	ds_read_b32 v10, v7
	ds_read_b32 v11, v9 offset:252
	ds_read_u16 v136, v6
	ds_read_u16 v137, v6 offset:272
	ds_read_u16 v138, v6 offset:544
	ds_read_u16 v139, v6 offset:816
	ds_read_u16 v140, v6 offset:1088
	ds_read_u16 v141, v6 offset:1360
	ds_read_u16 v142, v6 offset:1632
	ds_read_u16 v143, v6 offset:1904
	ds_read_u16 v144, v6 offset:2176
	ds_read_u16 v145, v6 offset:2448
	ds_read_u16 v146, v6 offset:2720
	ds_read_u16 v147, v6 offset:2992
	ds_read_u16 v148, v6 offset:3264
	ds_read_u16 v149, v6 offset:3536
	ds_read_u16 v150, v6 offset:3808
	ds_read_u16 v151, v6 offset:4080
	ds_read_u16 v184, v6 offset:4352
	ds_read_u16 v185, v6 offset:4624
	ds_read_u16 v186, v6 offset:4896
	ds_read_u16 v187, v6 offset:5168
	ds_read_u16 v188, v6 offset:5440
	ds_read_u16 v189, v6 offset:5712
	ds_read_u16 v190, v6 offset:5984
	ds_read_u16 v191, v6 offset:6256
	ds_read_u16 v192, v6 offset:6528
	ds_read_u16 v193, v6 offset:6800
	ds_read_u16 v194, v6 offset:7072
	ds_read_u16 v195, v6 offset:7344
	ds_read_u16 v196, v6 offset:7616
	ds_read_u16 v197, v6 offset:7888
	ds_read_u16 v198, v6 offset:8160
	ds_read_u16 v199, v6 offset:8432
	v_lshrrev_b32_e32 v2, 4, v5
	v_lshl_add_u32 v2, v2, 1, s27
	v_lshlrev_b32_e32 v2, 10, v2
	v_and_b32_e32 v3, 15, v5
	v_lshl_add_u32 v2, v3, 4, v2
	s_add_u32 s4, s10, s16
	s_addc_u32 s5, s11, s17
	s_add_u32 s4, s4, 0x15800000
	s_addc_u32 s5, s5, 0
	s_waitcnt lgkmcnt(14)
	v_sub_f32_e32 v10, v11, v10
	v_mul_f32_e32 v10, 0x3fb8aa3b, v10
	v_exp_f32_e32 v10, v10
	s_nop 1
	s_waitcnt lgkmcnt(14)
	v_readlane_b32 s32, v10, 0
	v_readlane_b32 s33, v10, 1
	v_readlane_b32 s34, v10, 2
	v_readlane_b32 s35, v10, 3
	v_readlane_b32 s36, v10, 4
	v_readlane_b32 s37, v10, 5
	v_readlane_b32 s38, v10, 6
	v_readlane_b32 s39, v10, 7
	v_lshlrev_b32_e32 v136, 16, v136
	v_lshlrev_b32_e32 v137, 16, v137
	v_lshlrev_b32_e32 v138, 16, v138
	v_lshlrev_b32_e32 v139, 16, v139
	v_lshlrev_b32_e32 v140, 16, v140
	v_lshlrev_b32_e32 v141, 16, v141
	v_lshlrev_b32_e32 v142, 16, v142
	v_lshlrev_b32_e32 v143, 16, v143
	v_mul_f32_e32 v136, s32, v136
	v_mul_f32_e32 v137, s33, v137
	v_mul_f32_e32 v138, s34, v138
	v_mul_f32_e32 v139, s35, v139
	v_mul_f32_e32 v140, s36, v140
	v_mul_f32_e32 v141, s37, v141
	v_mul_f32_e32 v142, s38, v142
	v_mul_f32_e32 v143, s39, v143
	v_cvt_pk_bf16_f32 v12, v136, v137
	v_cvt_pk_bf16_f32 v13, v138, v139
	v_cvt_pk_bf16_f32 v14, v140, v141
	v_cvt_pk_bf16_f32 v15, v142, v143
	global_store_dwordx4 v2, v[12:15], s[4:5] nt
	s_waitcnt lgkmcnt(14)
	v_readlane_b32 s32, v10, 8
	v_readlane_b32 s33, v10, 9
	v_readlane_b32 s34, v10, 10
	v_readlane_b32 s35, v10, 11
	v_readlane_b32 s36, v10, 12
	v_readlane_b32 s37, v10, 13
	v_readlane_b32 s38, v10, 14
	v_readlane_b32 s39, v10, 15
	v_lshlrev_b32_e32 v144, 16, v144
	v_lshlrev_b32_e32 v145, 16, v145
	v_lshlrev_b32_e32 v146, 16, v146
	v_lshlrev_b32_e32 v147, 16, v147
	v_lshlrev_b32_e32 v148, 16, v148
	v_lshlrev_b32_e32 v149, 16, v149
	v_lshlrev_b32_e32 v150, 16, v150
	v_lshlrev_b32_e32 v151, 16, v151
	v_mul_f32_e32 v144, s32, v144
	v_mul_f32_e32 v145, s33, v145
	v_mul_f32_e32 v146, s34, v146
	v_mul_f32_e32 v147, s35, v147
	v_mul_f32_e32 v148, s36, v148
	v_mul_f32_e32 v149, s37, v149
	v_mul_f32_e32 v150, s38, v150
	v_mul_f32_e32 v151, s39, v151
	v_cvt_pk_bf16_f32 v16, v144, v145
	v_cvt_pk_bf16_f32 v17, v146, v147
	v_cvt_pk_bf16_f32 v18, v148, v149
	v_cvt_pk_bf16_f32 v19, v150, v151
	global_store_dwordx4 v2, v[16:19], s[4:5] offset:256 nt
	s_waitcnt lgkmcnt(8)
	v_readlane_b32 s32, v10, 16
	v_readlane_b32 s33, v10, 17
	v_readlane_b32 s34, v10, 18
	v_readlane_b32 s35, v10, 19
	v_readlane_b32 s36, v10, 20
	v_readlane_b32 s37, v10, 21
	v_readlane_b32 s38, v10, 22
	v_readlane_b32 s39, v10, 23
	v_lshlrev_b32_e32 v184, 16, v184
	v_lshlrev_b32_e32 v185, 16, v185
	v_lshlrev_b32_e32 v186, 16, v186
	v_lshlrev_b32_e32 v187, 16, v187
	v_lshlrev_b32_e32 v188, 16, v188
	v_lshlrev_b32_e32 v189, 16, v189
	v_lshlrev_b32_e32 v190, 16, v190
	v_lshlrev_b32_e32 v191, 16, v191
	v_mul_f32_e32 v184, s32, v184
	v_mul_f32_e32 v185, s33, v185
	v_mul_f32_e32 v186, s34, v186
	v_mul_f32_e32 v187, s35, v187
	v_mul_f32_e32 v188, s36, v188
	v_mul_f32_e32 v189, s37, v189
	v_mul_f32_e32 v190, s38, v190
	v_mul_f32_e32 v191, s39, v191
	v_cvt_pk_bf16_f32 v12, v184, v185
	v_cvt_pk_bf16_f32 v13, v186, v187
	v_cvt_pk_bf16_f32 v14, v188, v189
	v_cvt_pk_bf16_f32 v15, v190, v191
	global_store_dwordx4 v2, v[12:15], s[4:5] offset:512 nt
	s_waitcnt lgkmcnt(0)
	v_readlane_b32 s32, v10, 24
	v_readlane_b32 s33, v10, 25
	v_readlane_b32 s34, v10, 26
	v_readlane_b32 s35, v10, 27
	v_readlane_b32 s36, v10, 28
	v_readlane_b32 s37, v10, 29
	v_readlane_b32 s38, v10, 30
	v_readlane_b32 s39, v10, 31
	v_lshlrev_b32_e32 v192, 16, v192
	v_lshlrev_b32_e32 v193, 16, v193
	v_lshlrev_b32_e32 v194, 16, v194
	v_lshlrev_b32_e32 v195, 16, v195
	v_lshlrev_b32_e32 v196, 16, v196
	v_lshlrev_b32_e32 v197, 16, v197
	v_lshlrev_b32_e32 v198, 16, v198
	v_lshlrev_b32_e32 v199, 16, v199
	v_mul_f32_e32 v192, s32, v192
	v_mul_f32_e32 v193, s33, v193
	v_mul_f32_e32 v194, s34, v194
	v_mul_f32_e32 v195, s35, v195
	v_mul_f32_e32 v196, s36, v196
	v_mul_f32_e32 v197, s37, v197
	v_mul_f32_e32 v198, s38, v198
	v_mul_f32_e32 v199, s39, v199
	v_cvt_pk_bf16_f32 v16, v192, v193
	v_cvt_pk_bf16_f32 v17, v194, v195
	v_cvt_pk_bf16_f32 v18, v196, v197
	v_cvt_pk_bf16_f32 v19, v198, v199
	global_store_dwordx4 v2, v[16:19], s[4:5] offset:768 nt
	s_branch .Lpd_done
